# FFN-down GEMM phases: one-sleep start stagger for odd in-XCD blocks (same as in-proj), on top of v56
# speedup vs baseline: 1.0183x; 1.0183x over previous
.LBB0_111:
	s_and_b64 vcc, exec, s[14:15]
	s_cbranch_vccz .LBB0_139
	v_readlane_b32 s98, v255, 18
	s_bitcmp0_b32 s98, 3
	s_cbranch_scc1 .Lstag_skip_res
	s_sleep 0x7f
